# scan loop: counted vmcnt waits per step instead of vmcnt(0) drain each 5-step iteration
# speedup vs baseline: 1.0002x; 1.0002x over previous
; DI unsigned pack2(float lo, float hi) { f32x2_t v = {lo, hi}; bf16x2_t b = __builtin_convertvector(v, bf16x2_t); return __builtin_bit_cast(unsigned, b); }
; DI float bflo(unsigned u) { return __uint_as_float(u << 16); }
; DI float bfhi(unsigned u) { return __uint_as_float(u & 0xffff0000u); }
; #define PINM do { asm volatile("" ::: "memory"); __builtin_amdgcn_sched_barrier(0); } while (0)
; DI void scan_step(const ScanSlot& s, f32x4 (&acc)[4], u16* sst, int irow, int g) {
;     unsigned pk[4][2];
; #pragma unroll
;     for (int mt = 0; mt < 4; ++mt) { pk[mt][0] = pack2(acc[mt][0], acc[mt][1]); pk[mt][1] = pack2(acc[mt][2], acc[mt][3]); }
;     bf16x8 bfr[2];
; #pragma unroll
;     for (int ks = 0; ks < 2; ++ks) { uint4 w = {pk[2 * ks][0], pk[2 * ks][1], pk[2 * ks + 1][0], pk[2 * ks + 1][1]}; bfr[ks] = __builtin_bit_cast(bf16x8, w);
;         { typedef unsigned u32x4_ __attribute__((ext_vector_type(4))); const u32x4_ wv_ = {w.x, w.y, w.z, w.w}; __builtin_nontemporal_store(wv_, (u32x4_*)(sst + irow * 64 + 32 * ks + 8 * g)); } }
; #pragma unroll
;     for (int mt = 0; mt < 4; ++mt) {
;         const unsigned hx = (mt & 1) ? s.gh[mt >> 1].z : s.gh[mt >> 1].x, hy = (mt & 1) ? s.gh[mt >> 1].w : s.gh[mt >> 1].y;
;         f32x4 c = {bflo(hx), bfhi(hx), bflo(hy), bfhi(hy)};
; #pragma unroll
;         for (int ks = 0; ks < 2; ++ks) c = __builtin_amdgcn_mfma_f32_16x16x32_bf16(__builtin_bit_cast(bf16x8, s.ga[mt][ks]), bfr[ks], c, 0, 0, 0);
;         acc[mt] = c;
;     }
; DI void scan_item(const Params& p, int item, int lane) {
;     ...
;         for (int st = 0; st < 125; st += 5) {
;             const int u = u0 + st;
;             scan_step(s0, acc, SST + (size_t)u * 4096, irow, g);       PINM; scan_load(s0, GT, HH, min(u + 5, ul), irow, i16, g); PINM;
;             scan_step(s1, acc, SST + (size_t)(u + 1) * 4096, irow, g); PINM; scan_load(s1, GT, HH, min(u + 6, ul), irow, i16, g); PINM;
;             scan_step(s2, acc, SST + (size_t)(u + 2) * 4096, irow, g); PINM; scan_load(s2, GT, HH, min(u + 7, ul), irow, i16, g); PINM;
;             scan_step(s3, acc, SST + (size_t)(u + 3) * 4096, irow, g); PINM; scan_load(s3, GT, HH, min(u + 8, ul), irow, i16, g); PINM;
;             scan_step(s4, acc, SST + (size_t)(u + 4) * 4096, irow, g); PINM; scan_load(s4, GT, HH, min(u + 9, ul), irow, i16, g); PINM;
.LBB0_438:
	v_cvt_pk_bf16_f32 v206, v206, v207
	v_cvt_pk_bf16_f32 v207, v208, v209
	v_cvt_pk_bf16_f32 v208, v214, v215
	v_cvt_pk_bf16_f32 v209, v216, v217
	s_cmp_lg_u32 s6, -5
	s_cbranch_scc1 .Lscan_w0
	s_waitcnt vmcnt(40)
.Lscan_w0:
	s_waitcnt vmcnt(48)
	v_lshlrev_b32_e32 v214, 16, v110
	v_and_b32_e32 v215, 0xffff0000, v110
	v_lshlrev_b32_e32 v216, 16, v111
	v_and_b32_e32 v217, 0xffff0000, v111
	v_cvt_pk_bf16_f32 v202, v202, v203
	v_cvt_pk_bf16_f32 v203, v204, v205
	v_mfma_f32_16x16x32_bf16 v[106:109], v[106:109], v[206:209], v[214:217]
	v_cvt_pk_bf16_f32 v204, v210, v211
	v_cvt_pk_bf16_f32 v205, v212, v213
	s_nop 1
	v_mfma_f32_16x16x32_bf16 v[210:213], v[102:105], v[202:205], v[106:109]
	v_lshlrev_b32_e32 v102, 16, v112
	v_and_b32_e32 v103, 0xffff0000, v112
	v_lshlrev_b32_e32 v104, 16, v113
	v_and_b32_e32 v105, 0xffff0000, v113
	s_nop 1
	v_mfma_f32_16x16x32_bf16 v[90:93], v[90:93], v[206:209], v[102:105]
	v_mfma_f32_16x16x32_bf16 v[214:217], v[86:89], v[202:205], v[90:93]
	v_lshlrev_b32_e32 v86, 16, v98
	v_and_b32_e32 v87, 0xffff0000, v98
	v_lshlrev_b32_e32 v88, 16, v99
	v_and_b32_e32 v89, 0xffff0000, v99
	s_nop 1
	v_mfma_f32_16x16x32_bf16 v[82:85], v[82:85], v[206:209], v[86:89]
	v_mfma_f32_16x16x32_bf16 v[232:235], v[78:81], v[202:205], v[82:85]
	v_lshlrev_b32_e32 v78, 16, v100
	v_and_b32_e32 v79, 0xffff0000, v100
	v_lshlrev_b32_e32 v80, 16, v101
	v_and_b32_e32 v81, 0xffff0000, v101
	s_nop 1
	v_mfma_f32_16x16x32_bf16 v[62:65], v[62:65], v[206:209], v[78:81]
	s_nop 2
	v_add_co_u32_e32 v78, vcc, s7, v230
	s_nop 1
	v_addc_co_u32_e32 v79, vcc, -1, v231, vcc
	global_store_dwordx4 v[78:79], v[206:209], off offset:-64 nt
	global_store_dwordx4 v[78:79], v[202:205], off nt
	s_nop 1
	v_mfma_f32_16x16x32_bf16 v[202:205], v[50:53], v[202:205], v[62:65]
	s_add_i32 s14, s8, s6
	s_add_i32 s0, s14, 10
	s_min_u32 s0, s0, s10
	s_lshl_b32 s0, s0, 13
	v_lshl_add_u64 v[50:51], v[226:227], 0, s[0:1]
	global_load_dwordx4 v[106:109], v[50:51], off
	global_load_dwordx4 v[102:105], v[50:51], off offset:64
	global_load_dwordx4 v[90:93], v[50:51], off offset:2048
	global_load_dwordx4 v[86:89], v[50:51], off offset:2112
	v_add_co_u32_e32 v50, vcc, s9, v50
	v_lshl_add_u64 v[98:99], v[228:229], 0, s[0:1]
	s_nop 0
	v_addc_co_u32_e32 v51, vcc, 0, v51, vcc
	global_load_dwordx4 v[82:85], v[50:51], off
	global_load_dwordx4 v[78:81], v[50:51], off offset:64
	global_load_dwordx4 v[62:65], v[50:51], off offset:2048
	s_nop 0
	global_load_dwordx4 v[50:53], v[50:51], off offset:2112
	s_nop 0
	global_load_dwordx4 v[110:113], v[98:99], off
	s_nop 0
	global_load_dwordx4 v[98:101], v[98:99], off offset:64
	s_cmp_lg_u32 s6, -5
	s_cbranch_scc1 .Lscan_w1
	s_waitcnt vmcnt(42)
.Lscan_w1:
	s_waitcnt vmcnt(48)
	v_cvt_pk_bf16_f32 v206, v210, v211
	v_cvt_pk_bf16_f32 v207, v212, v213
	v_cvt_pk_bf16_f32 v208, v214, v215
	v_cvt_pk_bf16_f32 v209, v216, v217
	v_lshlrev_b32_e32 v212, 16, v94
	v_and_b32_e32 v213, 0xffff0000, v94
	v_lshlrev_b32_e32 v214, 16, v95
	v_and_b32_e32 v215, 0xffff0000, v95
	v_cvt_pk_bf16_f32 v210, v232, v233
	v_cvt_pk_bf16_f32 v211, v234, v235
	v_mfma_f32_16x16x32_bf16 v[74:77], v[74:77], v[206:209], v[212:215]
	s_nop 2
	v_cvt_pk_bf16_f32 v212, v202, v203
	v_cvt_pk_bf16_f32 v213, v204, v205
	s_nop 1
	v_mfma_f32_16x16x32_bf16 v[202:205], v[70:73], v[210:213], v[74:77]
	v_lshlrev_b32_e32 v70, 16, v96
	v_and_b32_e32 v71, 0xffff0000, v96
	v_lshlrev_b32_e32 v72, 16, v97
	v_and_b32_e32 v73, 0xffff0000, v97
	s_nop 1
	v_mfma_f32_16x16x32_bf16 v[54:57], v[54:57], v[206:209], v[70:73]
	v_mfma_f32_16x16x32_bf16 v[214:217], v[58:61], v[210:213], v[54:57]
	s_nop 6
	v_lshlrev_b32_e32 v54, 16, v66
	v_and_b32_e32 v55, 0xffff0000, v66
	v_lshlrev_b32_e32 v56, 16, v67
	v_and_b32_e32 v57, 0xffff0000, v67
	s_nop 1
	v_mfma_f32_16x16x32_bf16 v[46:49], v[46:49], v[206:209], v[54:57]
	v_mfma_f32_16x16x32_bf16 v[232:235], v[42:45], v[210:213], v[46:49]
	v_lshlrev_b32_e32 v42, 16, v68
	v_and_b32_e32 v43, 0xffff0000, v68
	v_lshlrev_b32_e32 v44, 16, v69
	v_and_b32_e32 v45, 0xffff0000, v69
	s_nop 1
	v_mfma_f32_16x16x32_bf16 v[30:33], v[30:33], v[206:209], v[42:45]
	s_nop 2
	v_add_co_u32_e32 v42, vcc, s11, v230
	s_nop 1
	v_addc_co_u32_e32 v43, vcc, -1, v231, vcc
	global_store_dwordx4 v[42:43], v[206:209], off offset:-64 nt
	global_store_dwordx4 v[42:43], v[210:213], off nt
	s_nop 0
	v_mfma_f32_16x16x32_bf16 v[206:209], v[26:29], v[210:213], v[30:33]
	s_add_i32 s0, s14, 11
	s_min_u32 s0, s0, s10
	s_lshl_b32 s0, s0, 13
	v_lshl_add_u64 v[26:27], v[226:227], 0, s[0:1]
	global_load_dwordx4 v[74:77], v[26:27], off
	global_load_dwordx4 v[70:73], v[26:27], off offset:64
	global_load_dwordx4 v[54:57], v[26:27], off offset:2048
	global_load_dwordx4 v[58:61], v[26:27], off offset:2112
	v_add_co_u32_e32 v26, vcc, s9, v26
	v_lshl_add_u64 v[66:67], v[228:229], 0, s[0:1]
	s_nop 0
	v_addc_co_u32_e32 v27, vcc, 0, v27, vcc
	global_load_dwordx4 v[46:49], v[26:27], off
	global_load_dwordx4 v[42:45], v[26:27], off offset:64
	global_load_dwordx4 v[30:33], v[26:27], off offset:2048
	s_nop 0
	global_load_dwordx4 v[26:29], v[26:27], off offset:2112
	s_nop 0
	global_load_dwordx4 v[94:97], v[66:67], off
	s_nop 0
	global_load_dwordx4 v[66:69], v[66:67], off offset:64
	s_cmp_lg_u32 s6, -5
	s_cbranch_scc1 .Lscan_w2
	s_waitcnt vmcnt(44)
; DI unsigned pack2(float lo, float hi) { f32x2_t v = {lo, hi}; bf16x2_t b = __builtin_convertvector(v, bf16x2_t); return __builtin_bit_cast(unsigned, b); }
; DI float bflo(unsigned u) { return __uint_as_float(u << 16); }
; DI float bfhi(unsigned u) { return __uint_as_float(u & 0xffff0000u); }
; #define PINM do { asm volatile("" ::: "memory"); __builtin_amdgcn_sched_barrier(0); } while (0)
; DI void scan_step(const ScanSlot& s, f32x4 (&acc)[4], u16* sst, int irow, int g) {
;     unsigned pk[4][2];
; #pragma unroll
;     for (int mt = 0; mt < 4; ++mt) { pk[mt][0] = pack2(acc[mt][0], acc[mt][1]); pk[mt][1] = pack2(acc[mt][2], acc[mt][3]); }
;     bf16x8 bfr[2];
; #pragma unroll
;     for (int ks = 0; ks < 2; ++ks) { uint4 w = {pk[2 * ks][0], pk[2 * ks][1], pk[2 * ks + 1][0], pk[2 * ks + 1][1]}; bfr[ks] = __builtin_bit_cast(bf16x8, w);
;         { typedef unsigned u32x4_ __attribute__((ext_vector_type(4))); const u32x4_ wv_ = {w.x, w.y, w.z, w.w}; __builtin_nontemporal_store(wv_, (u32x4_*)(sst + irow * 64 + 32 * ks + 8 * g)); } }
; #pragma unroll
;     for (int mt = 0; mt < 4; ++mt) {
;         const unsigned hx = (mt & 1) ? s.gh[mt >> 1].z : s.gh[mt >> 1].x, hy = (mt & 1) ? s.gh[mt >> 1].w : s.gh[mt >> 1].y;
;         f32x4 c = {bflo(hx), bfhi(hx), bflo(hy), bfhi(hy)};
; #pragma unroll
;         for (int ks = 0; ks < 2; ++ks) c = __builtin_amdgcn_mfma_f32_16x16x32_bf16(__builtin_bit_cast(bf16x8, s.ga[mt][ks]), bfr[ks], c, 0, 0, 0);
;         acc[mt] = c;
;     }
; DI void scan_item(const Params& p, int item, int lane) {
;     ...
;         for (int st = 0; st < 125; st += 5) {
;             const int u = u0 + st;
;             scan_step(s0, acc, SST + (size_t)u * 4096, irow, g);       PINM; scan_load(s0, GT, HH, min(u + 5, ul), irow, i16, g); PINM;
;             scan_step(s1, acc, SST + (size_t)(u + 1) * 4096, irow, g); PINM; scan_load(s1, GT, HH, min(u + 6, ul), irow, i16, g); PINM;
;             scan_step(s2, acc, SST + (size_t)(u + 2) * 4096, irow, g); PINM; scan_load(s2, GT, HH, min(u + 7, ul), irow, i16, g); PINM;
;             scan_step(s3, acc, SST + (size_t)(u + 3) * 4096, irow, g); PINM; scan_load(s3, GT, HH, min(u + 8, ul), irow, i16, g); PINM;
;             scan_step(s4, acc, SST + (size_t)(u + 4) * 4096, irow, g); PINM; scan_load(s4, GT, HH, min(u + 9, ul), irow, i16, g); PINM;
.Lscan_w2:
	s_waitcnt vmcnt(48)
	v_cvt_pk_bf16_f32 v202, v202, v203
	v_cvt_pk_bf16_f32 v203, v204, v205
	v_cvt_pk_bf16_f32 v204, v214, v215
	v_cvt_pk_bf16_f32 v205, v216, v217
	v_lshlrev_b32_e32 v212, 16, v118
	v_and_b32_e32 v213, 0xffff0000, v118
	v_lshlrev_b32_e32 v214, 16, v119
	v_and_b32_e32 v215, 0xffff0000, v119
	v_cvt_pk_bf16_f32 v210, v232, v233
	v_cvt_pk_bf16_f32 v211, v234, v235
	v_mfma_f32_16x16x32_bf16 v[38:41], v[38:41], v[202:205], v[212:215]
	s_nop 2
	v_cvt_pk_bf16_f32 v212, v206, v207
	v_cvt_pk_bf16_f32 v213, v208, v209
	s_nop 1
	v_mfma_f32_16x16x32_bf16 v[206:209], v[34:37], v[210:213], v[38:41]
	v_lshlrev_b32_e32 v34, 16, v120
	v_and_b32_e32 v35, 0xffff0000, v120
	v_lshlrev_b32_e32 v36, 16, v121
	v_and_b32_e32 v37, 0xffff0000, v121
	s_nop 1
	v_mfma_f32_16x16x32_bf16 v[22:25], v[22:25], v[202:205], v[34:37]
	v_mfma_f32_16x16x32_bf16 v[214:217], v[18:21], v[210:213], v[22:25]
	v_lshlrev_b32_e32 v18, 16, v114
	v_and_b32_e32 v19, 0xffff0000, v114
	v_lshlrev_b32_e32 v20, 16, v115
	v_and_b32_e32 v21, 0xffff0000, v115
	s_nop 1
	v_mfma_f32_16x16x32_bf16 v[14:17], v[14:17], v[202:205], v[18:21]
	v_mfma_f32_16x16x32_bf16 v[232:235], v[10:13], v[210:213], v[14:17]
	v_lshlrev_b32_e32 v10, 16, v116
	v_and_b32_e32 v11, 0xffff0000, v116
	v_lshlrev_b32_e32 v12, 16, v117
	v_and_b32_e32 v13, 0xffff0000, v117
	s_nop 1
	v_mfma_f32_16x16x32_bf16 v[6:9], v[6:9], v[202:205], v[10:13]
	s_nop 2
	v_add_co_u32_e32 v10, vcc, s12, v230
	s_nop 1
	v_addc_co_u32_e32 v11, vcc, -1, v231, vcc
	global_store_dwordx4 v[10:11], v[202:205], off offset:-64 nt
	global_store_dwordx4 v[10:11], v[210:213], off nt
	s_nop 0
	v_mfma_f32_16x16x32_bf16 v[202:205], v[2:5], v[210:213], v[6:9]
	s_add_i32 s0, s14, 12
	s_min_u32 s0, s0, s10
	s_lshl_b32 s0, s0, 13
	v_lshl_add_u64 v[2:3], v[226:227], 0, s[0:1]
	global_load_dwordx4 v[38:41], v[2:3], off
	global_load_dwordx4 v[34:37], v[2:3], off offset:64
	global_load_dwordx4 v[22:25], v[2:3], off offset:2048
	global_load_dwordx4 v[18:21], v[2:3], off offset:2112
	v_add_co_u32_e32 v2, vcc, s9, v2
	v_lshl_add_u64 v[114:115], v[228:229], 0, s[0:1]
	s_nop 0
	v_addc_co_u32_e32 v3, vcc, 0, v3, vcc
	global_load_dwordx4 v[14:17], v[2:3], off
	global_load_dwordx4 v[10:13], v[2:3], off offset:64
	global_load_dwordx4 v[6:9], v[2:3], off offset:2048
	s_nop 0
	global_load_dwordx4 v[2:5], v[2:3], off offset:2112
	s_nop 0
	global_load_dwordx4 v[118:121], v[114:115], off
	s_nop 0
	global_load_dwordx4 v[114:117], v[114:115], off offset:64
	s_cmp_lg_u32 s6, -5
	s_cbranch_scc1 .Lscan_w3
	s_waitcnt vmcnt(46)
.Lscan_w3:
	s_waitcnt vmcnt(48)
	v_cvt_pk_bf16_f32 v206, v206, v207
	v_cvt_pk_bf16_f32 v207, v208, v209
	v_cvt_pk_bf16_f32 v208, v214, v215
	v_cvt_pk_bf16_f32 v209, v216, v217
	v_lshlrev_b32_e32 v212, 16, v194
	v_and_b32_e32 v213, 0xffff0000, v194
	v_lshlrev_b32_e32 v214, 16, v195
	v_and_b32_e32 v215, 0xffff0000, v195
	v_cvt_pk_bf16_f32 v210, v232, v233
	v_cvt_pk_bf16_f32 v211, v234, v235
	v_mfma_f32_16x16x32_bf16 v[178:181], v[178:181], v[206:209], v[212:215]
	s_nop 2
	v_cvt_pk_bf16_f32 v212, v202, v203
	v_cvt_pk_bf16_f32 v213, v204, v205
	s_nop 1
	v_mfma_f32_16x16x32_bf16 v[202:205], v[162:165], v[210:213], v[178:181]
	v_lshlrev_b32_e32 v162, 16, v196
	v_and_b32_e32 v163, 0xffff0000, v196
	v_lshlrev_b32_e32 v164, 16, v197
	v_and_b32_e32 v165, 0xffff0000, v197
	s_nop 1
	v_mfma_f32_16x16x32_bf16 v[146:149], v[146:149], v[206:209], v[162:165]
	v_mfma_f32_16x16x32_bf16 v[214:217], v[150:153], v[210:213], v[146:149]
	s_nop 6
	v_lshlrev_b32_e32 v146, 16, v166
	v_and_b32_e32 v147, 0xffff0000, v166
	v_lshlrev_b32_e32 v148, 16, v167
	v_and_b32_e32 v149, 0xffff0000, v167
	s_nop 1
	v_mfma_f32_16x16x32_bf16 v[130:133], v[130:133], v[206:209], v[146:149]
	v_mfma_f32_16x16x32_bf16 v[232:235], v[138:141], v[210:213], v[130:133]
	s_nop 6
	v_lshlrev_b32_e32 v130, 16, v168
	v_and_b32_e32 v131, 0xffff0000, v168
	v_lshlrev_b32_e32 v132, 16, v169
	v_and_b32_e32 v133, 0xffff0000, v169
	s_nop 1
	v_mfma_f32_16x16x32_bf16 v[126:129], v[126:129], v[206:209], v[130:133]
	s_nop 2
	v_add_co_u32_e32 v130, vcc, s13, v230
	s_nop 1
	v_addc_co_u32_e32 v131, vcc, -1, v231, vcc
	global_store_dwordx4 v[130:131], v[206:209], off offset:-64 nt
	global_store_dwordx4 v[130:131], v[210:213], off nt
	s_nop 0
	v_mfma_f32_16x16x32_bf16 v[206:209], v[122:125], v[210:213], v[126:129]
	s_add_i32 s0, s14, 13
	s_min_u32 s0, s0, s10
	s_lshl_b32 s0, s0, 13
	v_lshl_add_u64 v[122:123], v[226:227], 0, s[0:1]
	global_load_dwordx4 v[178:181], v[122:123], off
	global_load_dwordx4 v[162:165], v[122:123], off offset:64
	global_load_dwordx4 v[146:149], v[122:123], off offset:2048
	global_load_dwordx4 v[150:153], v[122:123], off offset:2112
	v_add_co_u32_e32 v122, vcc, s9, v122
	v_lshl_add_u64 v[166:167], v[228:229], 0, s[0:1]
	s_nop 0
	v_addc_co_u32_e32 v123, vcc, 0, v123, vcc
	global_load_dwordx4 v[130:133], v[122:123], off
	global_load_dwordx4 v[138:141], v[122:123], off offset:64
	global_load_dwordx4 v[126:129], v[122:123], off offset:2048
	s_nop 0
	global_load_dwordx4 v[122:125], v[122:123], off offset:2112
	s_nop 0
	global_load_dwordx4 v[194:197], v[166:167], off
	s_nop 0
	global_load_dwordx4 v[166:169], v[166:167], off offset:64
	s_waitcnt vmcnt(48)
; DI unsigned pack2(float lo, float hi) { f32x2_t v = {lo, hi}; bf16x2_t b = __builtin_convertvector(v, bf16x2_t); return __builtin_bit_cast(unsigned, b); }
; DI float bflo(unsigned u) { return __uint_as_float(u << 16); }
; DI float bfhi(unsigned u) { return __uint_as_float(u & 0xffff0000u); }
; #define PINM do { asm volatile("" ::: "memory"); __builtin_amdgcn_sched_barrier(0); } while (0)
; DI void scan_step(const ScanSlot& s, f32x4 (&acc)[4], u16* sst, int irow, int g) {
;     unsigned pk[4][2];
; #pragma unroll
;     for (int mt = 0; mt < 4; ++mt) { pk[mt][0] = pack2(acc[mt][0], acc[mt][1]); pk[mt][1] = pack2(acc[mt][2], acc[mt][3]); }
;     bf16x8 bfr[2];
; #pragma unroll
;     for (int ks = 0; ks < 2; ++ks) { uint4 w = {pk[2 * ks][0], pk[2 * ks][1], pk[2 * ks + 1][0], pk[2 * ks + 1][1]}; bfr[ks] = __builtin_bit_cast(bf16x8, w);
;         { typedef unsigned u32x4_ __attribute__((ext_vector_type(4))); const u32x4_ wv_ = {w.x, w.y, w.z, w.w}; __builtin_nontemporal_store(wv_, (u32x4_*)(sst + irow * 64 + 32 * ks + 8 * g)); } }
; #pragma unroll
;     for (int mt = 0; mt < 4; ++mt) {
;         const unsigned hx = (mt & 1) ? s.gh[mt >> 1].z : s.gh[mt >> 1].x, hy = (mt & 1) ? s.gh[mt >> 1].w : s.gh[mt >> 1].y;
;         f32x4 c = {bflo(hx), bfhi(hx), bflo(hy), bfhi(hy)};
; #pragma unroll
;         for (int ks = 0; ks < 2; ++ks) c = __builtin_amdgcn_mfma_f32_16x16x32_bf16(__builtin_bit_cast(bf16x8, s.ga[mt][ks]), bfr[ks], c, 0, 0, 0);
;         acc[mt] = c;
;     }
; DI void scan_item(const Params& p, int item, int lane) {
;     ...
;             scan_step(s4, acc, SST + (size_t)(u + 4) * 4096, irow, g); PINM; scan_load(s4, GT, HH, min(u + 9, ul), irow, i16, g); PINM;
;         }
	v_cvt_pk_bf16_f32 v210, v202, v203
	v_cvt_pk_bf16_f32 v211, v204, v205
	v_cvt_pk_bf16_f32 v212, v214, v215
	v_cvt_pk_bf16_f32 v213, v216, v217
	v_lshlrev_b32_e32 v202, 16, v198
	v_and_b32_e32 v203, 0xffff0000, v198
	v_lshlrev_b32_e32 v204, 16, v199
	v_and_b32_e32 v205, 0xffff0000, v199
	v_cvt_pk_bf16_f32 v232, v232, v233
	v_cvt_pk_bf16_f32 v233, v234, v235
	v_mfma_f32_16x16x32_bf16 v[190:193], v[190:193], v[210:213], v[202:205]
	v_cvt_pk_bf16_f32 v234, v206, v207
	v_cvt_pk_bf16_f32 v235, v208, v209
	global_store_dwordx4 v[230:231], v[210:213], off offset:-64 nt
	global_store_dwordx4 v[230:231], v[232:235], off nt
	v_mfma_f32_16x16x32_bf16 v[206:209], v[182:185], v[232:235], v[190:193]
	v_lshlrev_b32_e32 v182, 16, v200
	v_and_b32_e32 v183, 0xffff0000, v200
	v_lshlrev_b32_e32 v184, 16, v201
	v_and_b32_e32 v185, 0xffff0000, v201
	s_nop 1
	v_mfma_f32_16x16x32_bf16 v[170:173], v[170:173], v[210:213], v[182:185]
	v_mfma_f32_16x16x32_bf16 v[214:217], v[174:177], v[232:235], v[170:173]
	s_nop 6
	v_lshlrev_b32_e32 v170, 16, v186
	v_and_b32_e32 v171, 0xffff0000, v186
	v_lshlrev_b32_e32 v172, 16, v187
	v_and_b32_e32 v173, 0xffff0000, v187
	s_nop 1
	v_mfma_f32_16x16x32_bf16 v[154:157], v[154:157], v[210:213], v[170:173]
	v_mfma_f32_16x16x32_bf16 v[202:205], v[158:161], v[232:235], v[154:157]
	s_nop 6
	v_lshlrev_b32_e32 v154, 16, v188
	v_and_b32_e32 v155, 0xffff0000, v188
	v_lshlrev_b32_e32 v156, 16, v189
	v_and_b32_e32 v157, 0xffff0000, v189
	s_nop 1
	v_mfma_f32_16x16x32_bf16 v[142:145], v[142:145], v[210:213], v[154:157]
	v_mfma_f32_16x16x32_bf16 v[210:213], v[134:137], v[232:235], v[142:145]
	s_add_i32 s14, s14, 14
	s_min_u32 s0, s14, s10
	s_lshl_b32 s0, s0, 13
	v_lshl_add_u64 v[134:135], v[226:227], 0, s[0:1]
	global_load_dwordx4 v[190:193], v[134:135], off
	global_load_dwordx4 v[182:185], v[134:135], off offset:64
	global_load_dwordx4 v[170:173], v[134:135], off offset:2048
	global_load_dwordx4 v[174:177], v[134:135], off offset:2112
	v_add_co_u32_e32 v134, vcc, s9, v134
	v_lshl_add_u64 v[186:187], v[228:229], 0, s[0:1]
	s_nop 0
	v_addc_co_u32_e32 v135, vcc, 0, v135, vcc
	global_load_dwordx4 v[154:157], v[134:135], off
	global_load_dwordx4 v[158:161], v[134:135], off offset:64
	global_load_dwordx4 v[142:145], v[134:135], off offset:2048
	s_nop 0
	global_load_dwordx4 v[134:137], v[134:135], off offset:2112
	s_nop 0
	global_load_dwordx4 v[198:201], v[186:187], off
	s_nop 0
	global_load_dwordx4 v[186:189], v[186:187], off offset:64
	s_add_i32 s6, s6, 5
	s_cmpk_gt_u32 s6, 0x77
	v_lshl_add_u64 v[230:231], v[230:231], 0, s[4:5]
	s_cbranch_scc0 .LBB0_438
; DI unsigned pack2(float lo, float hi) { f32x2_t v = {lo, hi}; bf16x2_t b = __builtin_convertvector(v, bf16x2_t); return __builtin_bit_cast(unsigned, b); }
; DI float bflo(unsigned u) { return __uint_as_float(u << 16); }
; DI float bfhi(unsigned u) { return __uint_as_float(u & 0xffff0000u); }
; #define PINM do { asm volatile("" ::: "memory"); __builtin_amdgcn_sched_barrier(0); } while (0)
; DI void scan_step(const ScanSlot& s, f32x4 (&acc)[4], u16* sst, int irow, int g) {
;     unsigned pk[4][2];
; #pragma unroll
;     for (int mt = 0; mt < 4; ++mt) { pk[mt][0] = pack2(acc[mt][0], acc[mt][1]); pk[mt][1] = pack2(acc[mt][2], acc[mt][3]); }
;     bf16x8 bfr[2];
; #pragma unroll
;     for (int ks = 0; ks < 2; ++ks) { uint4 w = {pk[2 * ks][0], pk[2 * ks][1], pk[2 * ks + 1][0], pk[2 * ks + 1][1]}; bfr[ks] = __builtin_bit_cast(bf16x8, w);
;         { typedef unsigned u32x4_ __attribute__((ext_vector_type(4))); const u32x4_ wv_ = {w.x, w.y, w.z, w.w}; __builtin_nontemporal_store(wv_, (u32x4_*)(sst + irow * 64 + 32 * ks + 8 * g)); } }
; #pragma unroll
;     for (int mt = 0; mt < 4; ++mt) {
;         const unsigned hx = (mt & 1) ? s.gh[mt >> 1].z : s.gh[mt >> 1].x, hy = (mt & 1) ? s.gh[mt >> 1].w : s.gh[mt >> 1].y;
;         f32x4 c = {bflo(hx), bfhi(hx), bflo(hy), bfhi(hy)};
; #pragma unroll
;         for (int ks = 0; ks < 2; ++ks) c = __builtin_amdgcn_mfma_f32_16x16x32_bf16(__builtin_bit_cast(bf16x8, s.ga[mt][ks]), bfr[ks], c, 0, 0, 0);
;         acc[mt] = c;
;     }
; DI void scan_item(const Params& p, int item, int lane) {
;     ...
;         scan_step(s0, acc, SST + (size_t)(u0 + 125) * 4096, irow, g); PINM;
;         scan_step(s1, acc, SST + (size_t)(u0 + 126) * 4096, irow, g); PINM;
;         scan_step(s2, acc, SST + (size_t)(u0 + 127) * 4096, irow, g);
;     ...
;         float* fout = p.out + O_SP + (size_t)bh * 4096;
; #pragma unroll
;         for (int mt = 0; mt < 4; ++mt) *(f32x4*)(fout + irow * 64 + 16 * mt + 4 * g) = acc[mt];
	s_waitcnt vmcnt(0)
	v_cvt_pk_bf16_f32 v122, v206, v207
	v_cvt_pk_bf16_f32 v123, v208, v209
	v_cvt_pk_bf16_f32 v124, v214, v215
	v_cvt_pk_bf16_f32 v125, v216, v217
	v_lshlrev_b32_e32 v130, 16, v110
	v_and_b32_e32 v131, 0xffff0000, v110
	v_lshlrev_b32_e32 v132, 16, v111
	v_and_b32_e32 v133, 0xffff0000, v111
	v_cvt_pk_bf16_f32 v126, v202, v203
	v_cvt_pk_bf16_f32 v127, v204, v205
	v_mfma_f32_16x16x32_bf16 v[106:109], v[106:109], v[122:125], v[130:133]
	v_cvt_pk_bf16_f32 v128, v210, v211
	v_cvt_pk_bf16_f32 v129, v212, v213
	s_add_u32 s0, s54, 0xea14800
	s_addc_u32 s1, s55, 0
	v_mfma_f32_16x16x32_bf16 v[102:105], v[102:105], v[126:129], v[106:109]
	s_add_u32 s4, s0, s3
	s_addc_u32 s5, s1, 0
	v_lshlrev_b32_e32 v110, 1, v222
	v_lshlrev_b32_e32 v106, 16, v112
	v_and_b32_e32 v107, 0xffff0000, v112
	v_lshlrev_b32_e32 v108, 16, v113
	v_and_b32_e32 v109, 0xffff0000, v113
	v_mov_b32_e32 v111, 0
	v_lshlrev_b32_e32 v130, 1, v224
	v_mfma_f32_16x16x32_bf16 v[90:93], v[90:93], v[122:125], v[106:109]
	v_mov_b32_e32 v131, v111
	s_mov_b32 s3, 0xfa000
	v_mfma_f32_16x16x32_bf16 v[86:89], v[86:89], v[126:129], v[90:93]
	v_lshl_add_u64 v[106:107], s[4:5], 0, v[110:111]
	v_lshl_add_u64 v[106:107], v[106:107], 0, v[130:131]
	s_mov_b64 s[4:5], 0xfa000
	s_nop 1
	v_lshlrev_b32_e32 v90, 16, v98
	v_and_b32_e32 v91, 0xffff0000, v98
	v_lshlrev_b32_e32 v92, 16, v99
	v_and_b32_e32 v93, 0xffff0000, v99
	s_nop 1
	v_mfma_f32_16x16x32_bf16 v[82:85], v[82:85], v[122:125], v[90:93]
	v_mfma_f32_16x16x32_bf16 v[78:81], v[78:81], v[126:129], v[82:85]
	s_nop 1
	v_lshl_add_u64 v[90:91], v[106:107], 0, s[4:5]
	s_nop 3
	v_lshlrev_b32_e32 v82, 16, v100
	v_and_b32_e32 v83, 0xffff0000, v100
	v_lshlrev_b32_e32 v84, 16, v101
	v_and_b32_e32 v85, 0xffff0000, v101
	s_nop 1
	v_mfma_f32_16x16x32_bf16 v[62:65], v[62:65], v[122:125], v[82:85]
	s_nop 2
	v_add_co_u32_e32 v82, vcc, s3, v106
	v_mfma_f32_16x16x32_bf16 v[50:53], v[50:53], v[126:129], v[62:65]
	s_nop 0
	v_addc_co_u32_e32 v83, vcc, 0, v107, vcc
	global_store_dwordx4 v[82:83], v[122:125], off nt
	global_store_dwordx4 v[90:91], v[126:129], off offset:64 nt
	v_cvt_pk_bf16_f32 v62, v102, v103
	v_cvt_pk_bf16_f32 v63, v104, v105
	v_cvt_pk_bf16_f32 v64, v86, v87
	v_cvt_pk_bf16_f32 v65, v88, v89
	v_lshlrev_b32_e32 v82, 16, v94
	v_and_b32_e32 v83, 0xffff0000, v94
	v_lshlrev_b32_e32 v84, 16, v95
	v_and_b32_e32 v85, 0xffff0000, v95
	v_cvt_pk_bf16_f32 v78, v78, v79
	v_cvt_pk_bf16_f32 v79, v80, v81
	v_mfma_f32_16x16x32_bf16 v[74:77], v[74:77], v[62:65], v[82:85]
	v_cvt_pk_bf16_f32 v80, v50, v51
	v_cvt_pk_bf16_f32 v81, v52, v53
	s_mov_b32 s3, 0xfc000
	s_mov_b64 s[4:5], 0xfc000
	v_mfma_f32_16x16x32_bf16 v[50:53], v[70:73], v[78:81], v[74:77]
	v_lshlrev_b32_e32 v70, 16, v96
	v_and_b32_e32 v71, 0xffff0000, v96
	v_lshlrev_b32_e32 v72, 16, v97
	v_and_b32_e32 v73, 0xffff0000, v97
	s_nop 1
	v_mfma_f32_16x16x32_bf16 v[54:57], v[54:57], v[62:65], v[70:73]
	v_mfma_f32_16x16x32_bf16 v[54:57], v[58:61], v[78:81], v[54:57]
	v_lshlrev_b32_e32 v58, 16, v66
	v_and_b32_e32 v59, 0xffff0000, v66
	v_lshlrev_b32_e32 v60, 16, v67
	v_and_b32_e32 v61, 0xffff0000, v67
	s_nop 1
	v_mfma_f32_16x16x32_bf16 v[46:49], v[46:49], v[62:65], v[58:61]
	v_mfma_f32_16x16x32_bf16 v[42:45], v[42:45], v[78:81], v[46:49]
	s_nop 1
	v_lshl_add_u64 v[58:59], v[106:107], 0, s[4:5]
	s_nop 3
	v_lshlrev_b32_e32 v46, 16, v68
	v_and_b32_e32 v47, 0xffff0000, v68
	v_lshlrev_b32_e32 v48, 16, v69
	v_and_b32_e32 v49, 0xffff0000, v69
	s_nop 1
	v_mfma_f32_16x16x32_bf16 v[30:33], v[30:33], v[62:65], v[46:49]
	s_nop 2
	v_add_co_u32_e32 v46, vcc, s3, v106
	v_mfma_f32_16x16x32_bf16 v[26:29], v[26:29], v[78:81], v[30:33]
	s_nop 0
	v_addc_co_u32_e32 v47, vcc, 0, v107, vcc
	global_store_dwordx4 v[46:47], v[62:65], off nt
	global_store_dwordx4 v[58:59], v[78:81], off offset:64 nt
	v_cvt_pk_bf16_f32 v30, v50, v51
	v_cvt_pk_bf16_f32 v31, v52, v53
	v_cvt_pk_bf16_f32 v32, v54, v55
	v_cvt_pk_bf16_f32 v33, v56, v57
	v_lshlrev_b32_e32 v46, 16, v118
	v_and_b32_e32 v47, 0xffff0000, v118
	v_lshlrev_b32_e32 v48, 16, v119
	v_and_b32_e32 v49, 0xffff0000, v119
	v_cvt_pk_bf16_f32 v42, v42, v43
	v_cvt_pk_bf16_f32 v43, v44, v45
	v_mfma_f32_16x16x32_bf16 v[38:41], v[38:41], v[30:33], v[46:49]
	v_cvt_pk_bf16_f32 v44, v26, v27
	v_cvt_pk_bf16_f32 v45, v28, v29
	s_lshl_b32 s3, s10, 13
	s_add_u32 s0, s0, s3
	v_mfma_f32_16x16x32_bf16 v[26:29], v[34:37], v[42:45], v[38:41]
	v_lshlrev_b32_e32 v34, 16, v120
	v_and_b32_e32 v35, 0xffff0000, v120
	v_lshlrev_b32_e32 v36, 16, v121
	v_and_b32_e32 v37, 0xffff0000, v121
	s_addc_u32 s1, s1, 0
	s_nop 0
	v_mfma_f32_16x16x32_bf16 v[22:25], v[22:25], v[30:33], v[34:37]
	v_mfma_f32_16x16x32_bf16 v[18:21], v[18:21], v[42:45], v[22:25]
	s_nop 6
	v_lshlrev_b32_e32 v22, 16, v114
	v_and_b32_e32 v23, 0xffff0000, v114
	v_lshlrev_b32_e32 v24, 16, v115
	v_and_b32_e32 v25, 0xffff0000, v115
	s_nop 1
	v_mfma_f32_16x16x32_bf16 v[14:17], v[14:17], v[30:33], v[22:25]
	v_mfma_f32_16x16x32_bf16 v[10:13], v[10:13], v[42:45], v[14:17]
	s_nop 1
	v_lshl_add_u64 v[22:23], s[0:1], 0, v[110:111]
	s_lshl_b32 s0, s2, 12
	s_add_u32 s0, s52, s0
	s_nop 1
	v_lshlrev_b32_e32 v14, 16, v116
	v_and_b32_e32 v15, 0xffff0000, v116
	v_lshlrev_b32_e32 v16, 16, v117
	v_and_b32_e32 v17, 0xffff0000, v117
	s_addc_u32 s1, s53, 0
	v_lshlrev_b32_e32 v110, 2, v222
	v_mfma_f32_16x16x32_bf16 v[6:9], v[6:9], v[30:33], v[14:17]
	v_mfma_f32_16x16x32_bf16 v[2:5], v[2:5], v[42:45], v[6:9]
	s_nop 1
	v_lshl_add_u64 v[14:15], v[22:23], 0, v[130:131]
	global_store_dwordx4 v[14:15], v[30:33], off nt
	global_store_dwordx4 v[14:15], v[42:45], off offset:64 nt
	s_nop 1
	v_lshl_add_u64 v[6:7], s[0:1], 0, v[110:111]
	v_lshlrev_b32_e32 v110, 4, v225
	v_lshl_add_u64 v[6:7], v[6:7], 0, v[110:111]
	s_mov_b64 s[0:1], 0x4800000
	v_lshl_add_u64 v[8:9], v[6:7], 0, s[0:1]
	v_add_co_u32_e32 v6, vcc, 0x4800000, v6
	s_nop 1
	v_addc_co_u32_e32 v7, vcc, 0, v7, vcc
	global_store_dwordx4 v[6:7], v[26:29], off
	global_store_dwordx4 v[8:9], v[18:21], off offset:64
	global_store_dwordx4 v[8:9], v[10:13], off offset:128
	global_store_dwordx4 v[8:9], v[2:5], off offset:192
